# grid barrier: follower workgroups poll the top-level generation word directly instead of the per-XCD generation (one fewer atomic hop per barrier)
# speedup vs baseline: 1.0076x; 1.0015x over previous
; DI unsigned xb_ld(unsigned* p) { return __hip_atomic_load(p, __ATOMIC_RELAXED, __HIP_MEMORY_SCOPE_AGENT); }
; DI unsigned xb_add(unsigned* p, unsigned v) { return __hip_atomic_fetch_add(p, v, __ATOMIC_RELAXED, __HIP_MEMORY_SCOPE_AGENT); }
; #define XB_SPIN(cond, bar) do { unsigned _sp = 0; while (cond) { \
;     if ((++_sp & 255u) == 0u) { if (xb_ld(&(bar)[XB_TMO])) break; if (_sp > XB_SPIN_CAP) { atomicAdd(&(bar)[XB_TMO], 1u); break; } } } } while (0)
; DI void xcd_barrier(const XcdBarrier& b) {
;     ...
;     unsigned nloc = b.st[0], nx = b.st[1];
;     if (nloc == 0u) { xcd_barrier_complete(bar, b.x, nloc, nx); b.st[0] = nloc; b.st[1] = nx; }
;     const unsigned old = xb_add(&bar[XB_XSUB(b.x)], 1u);
;     const unsigned gen = old / nloc;
;     if (old + 1u == (gen + 1u) * nloc) {
;       __builtin_amdgcn_fence(__ATOMIC_RELEASE, "agent");
;       asm volatile("s_waitcnt vmcnt(0)" ::: "memory");
;       const unsigned og = xb_add(&bar[XB_TOP], 1u);
;       const unsigned tg = og / nx;
;       if (og + 1u == (tg + 1u) * nx) xb_add(&bar[XB_TOPGEN], 1u);
;       else XB_SPIN(xb_ld(&bar[XB_TOPGEN]) == tg, bar);
;       __builtin_amdgcn_fence(__ATOMIC_ACQUIRE, "agent");
;       xb_add(&bar[XB_XGEN(b.x)], 1u);
;       asm volatile("s_waitcnt vmcnt(0)" ::: "memory");
;     } else {
;       XB_SPIN(xb_ld(&bar[XB_XGEN(b.x)]) == gen, bar);
;       __builtin_amdgcn_fence(__ATOMIC_ACQUIRE, "agent");
;       asm volatile("s_waitcnt vmcnt(0)" ::: "memory");
;     }
.LBB0_319:
	s_or_b64 exec, exec, s[34:35]
	v_cvt_f32_u32_e32 v5, v3
	s_waitcnt vmcnt(0)
	v_readfirstlane_b32 s2, v4
	v_sub_u32_e32 v4, 0, v3
	v_rcp_iflag_f32_e32 v5, v5
	v_add_u32_e32 v6, s2, v0
	v_mul_f32_e32 v5, 0x4f7ffffe, v5
	v_cvt_u32_f32_e32 v5, v5
	v_mul_lo_u32 v0, v4, v5
	v_mul_hi_u32 v0, v5, v0
	v_add_u32_e32 v0, v5, v0
	v_mul_hi_u32 v0, v6, v0
	v_mul_lo_u32 v4, v0, v3
	v_sub_u32_e32 v4, v6, v4
	v_add_u32_e32 v5, 1, v0
	v_cmp_ge_u32_e32 vcc, v4, v3
	s_nop 1
	v_cndmask_b32_e32 v0, v0, v5, vcc
	v_sub_u32_e32 v5, v4, v3
	v_cndmask_b32_e32 v4, v4, v5, vcc
	v_add_u32_e32 v5, 1, v0
	v_cmp_ge_u32_e32 vcc, v4, v3
	v_add_u32_e32 v4, 1, v6
	s_nop 0
	v_cndmask_b32_e32 v0, v0, v5, vcc
	v_mul_lo_u32 v5, v3, v0
	v_add_u32_e32 v3, v5, v3
	v_cmp_ne_u32_e32 vcc, v4, v3
	s_and_saveexec_b64 s[8:9], vcc
	s_xor_b64 s[34:35], exec, s[8:9]
	s_cbranch_execz .LBB0_333
	v_readlane_b32 s8, v253, 62
	v_readlane_b32 s9, v253, 63
	s_waitcnt lgkmcnt(0)
	s_nop 3
	global_load_dword v2, v1, s[8:9] sc1
	s_waitcnt vmcnt(0)
	v_cmp_eq_u32_e32 vcc, v2, v0
	s_and_saveexec_b64 s[38:39], vcc
	s_cbranch_execz .LBB0_332
	s_mov_b32 s2, 1
	s_mov_b64 s[40:41], 0
	s_branch .LBB0_323

; DI unsigned xb_ld(unsigned* p) { return __hip_atomic_load(p, __ATOMIC_RELAXED, __HIP_MEMORY_SCOPE_AGENT); }
; DI unsigned xb_add(unsigned* p, unsigned v) { return __hip_atomic_fetch_add(p, v, __ATOMIC_RELAXED, __HIP_MEMORY_SCOPE_AGENT); }
; #define XB_SPIN(cond, bar) do { unsigned _sp = 0; while (cond) { \
;     if ((++_sp & 255u) == 0u) { if (xb_ld(&(bar)[XB_TMO])) break; if (_sp > XB_SPIN_CAP) { atomicAdd(&(bar)[XB_TMO], 1u); break; } } } } while (0)
; DI void xcd_barrier(const XcdBarrier& b) {
;     ...
;     unsigned nloc = b.st[0], nx = b.st[1];
;     if (nloc == 0u) { xcd_barrier_complete(bar, b.x, nloc, nx); b.st[0] = nloc; b.st[1] = nx; }
;     const unsigned old = xb_add(&bar[XB_XSUB(b.x)], 1u);
;     const unsigned gen = old / nloc;
;     if (old + 1u == (gen + 1u) * nloc) {
;       __builtin_amdgcn_fence(__ATOMIC_RELEASE, "agent");
;       asm volatile("s_waitcnt vmcnt(0)" ::: "memory");
;       const unsigned og = xb_add(&bar[XB_TOP], 1u);
;       const unsigned tg = og / nx;
;       if (og + 1u == (tg + 1u) * nx) xb_add(&bar[XB_TOPGEN], 1u);
;       else XB_SPIN(xb_ld(&bar[XB_TOPGEN]) == tg, bar);
;       __builtin_amdgcn_fence(__ATOMIC_ACQUIRE, "agent");
;       xb_add(&bar[XB_XGEN(b.x)], 1u);
;       asm volatile("s_waitcnt vmcnt(0)" ::: "memory");
;     } else {
;       XB_SPIN(xb_ld(&bar[XB_XGEN(b.x)]) == gen, bar);
;       __builtin_amdgcn_fence(__ATOMIC_ACQUIRE, "agent");
;       asm volatile("s_waitcnt vmcnt(0)" ::: "memory");
;     }
.LBB0_426:
	s_or_b64 exec, exec, s[34:35]
	v_cvt_f32_u32_e32 v5, v3
	s_waitcnt vmcnt(0)
	v_readfirstlane_b32 s8, v4
	v_sub_u32_e32 v4, 0, v3
	v_rcp_iflag_f32_e32 v5, v5
	v_add_u32_e32 v6, s8, v0
	v_mul_f32_e32 v5, 0x4f7ffffe, v5
	v_cvt_u32_f32_e32 v5, v5
	v_mul_lo_u32 v0, v4, v5
	v_mul_hi_u32 v0, v5, v0
	v_add_u32_e32 v0, v5, v0
	v_mul_hi_u32 v0, v6, v0
	v_mul_lo_u32 v4, v0, v3
	v_sub_u32_e32 v4, v6, v4
	v_add_u32_e32 v5, 1, v0
	v_cmp_ge_u32_e32 vcc, v4, v3
	s_nop 1
	v_cndmask_b32_e32 v0, v0, v5, vcc
	v_sub_u32_e32 v5, v4, v3
	v_cndmask_b32_e32 v4, v4, v5, vcc
	v_add_u32_e32 v5, 1, v0
	v_cmp_ge_u32_e32 vcc, v4, v3
	v_add_u32_e32 v4, 1, v6
	s_nop 0
	v_cndmask_b32_e32 v0, v0, v5, vcc
	v_mul_lo_u32 v5, v3, v0
	v_add_u32_e32 v3, v5, v3
	v_cmp_ne_u32_e32 vcc, v4, v3
	s_and_saveexec_b64 s[8:9], vcc
	s_xor_b64 s[34:35], exec, s[8:9]
	s_cbranch_execz .LBB0_440
	v_readlane_b32 s8, v253, 62
	v_readlane_b32 s9, v253, 63
	s_waitcnt lgkmcnt(0)
	s_nop 3
	global_load_dword v2, v1, s[8:9] sc1
	s_waitcnt vmcnt(0)
	v_cmp_eq_u32_e32 vcc, v2, v0
	s_and_saveexec_b64 s[40:41], vcc
	s_cbranch_execz .LBB0_439
	s_mov_b32 s8, 1
	s_mov_b64 s[42:43], 0
	s_branch .LBB0_430

; DI unsigned xb_ld(unsigned* p) { return __hip_atomic_load(p, __ATOMIC_RELAXED, __HIP_MEMORY_SCOPE_AGENT); }
; DI unsigned xb_add(unsigned* p, unsigned v) { return __hip_atomic_fetch_add(p, v, __ATOMIC_RELAXED, __HIP_MEMORY_SCOPE_AGENT); }
; #define XB_SPIN(cond, bar) do { unsigned _sp = 0; while (cond) { \
;     if ((++_sp & 255u) == 0u) { if (xb_ld(&(bar)[XB_TMO])) break; if (_sp > XB_SPIN_CAP) { atomicAdd(&(bar)[XB_TMO], 1u); break; } } } } while (0)
; DI void xcd_barrier(const XcdBarrier& b) {
;     ...
;     unsigned nloc = b.st[0], nx = b.st[1];
;     if (nloc == 0u) { xcd_barrier_complete(bar, b.x, nloc, nx); b.st[0] = nloc; b.st[1] = nx; }
;     const unsigned old = xb_add(&bar[XB_XSUB(b.x)], 1u);
;     const unsigned gen = old / nloc;
;     if (old + 1u == (gen + 1u) * nloc) {
;       __builtin_amdgcn_fence(__ATOMIC_RELEASE, "agent");
;       asm volatile("s_waitcnt vmcnt(0)" ::: "memory");
;       const unsigned og = xb_add(&bar[XB_TOP], 1u);
;       const unsigned tg = og / nx;
;       if (og + 1u == (tg + 1u) * nx) xb_add(&bar[XB_TOPGEN], 1u);
;       else XB_SPIN(xb_ld(&bar[XB_TOPGEN]) == tg, bar);
;       __builtin_amdgcn_fence(__ATOMIC_ACQUIRE, "agent");
;       xb_add(&bar[XB_XGEN(b.x)], 1u);
;       asm volatile("s_waitcnt vmcnt(0)" ::: "memory");
;     } else {
;       XB_SPIN(xb_ld(&bar[XB_XGEN(b.x)]) == gen, bar);
;       __builtin_amdgcn_fence(__ATOMIC_ACQUIRE, "agent");
;       asm volatile("s_waitcnt vmcnt(0)" ::: "memory");
;     }
.LBB0_624:
	s_or_b64 exec, exec, s[34:35]
	v_cvt_f32_u32_e32 v5, v3
	s_waitcnt vmcnt(0)
	v_readfirstlane_b32 s8, v4
	v_sub_u32_e32 v4, 0, v3
	v_rcp_iflag_f32_e32 v5, v5
	v_add_u32_e32 v6, s8, v0
	v_mul_f32_e32 v5, 0x4f7ffffe, v5
	v_cvt_u32_f32_e32 v5, v5
	v_mul_lo_u32 v0, v4, v5
	v_mul_hi_u32 v0, v5, v0
	v_add_u32_e32 v0, v5, v0
	v_mul_hi_u32 v0, v6, v0
	v_mul_lo_u32 v4, v0, v3
	v_sub_u32_e32 v4, v6, v4
	v_add_u32_e32 v5, 1, v0
	v_cmp_ge_u32_e32 vcc, v4, v3
	s_nop 1
	v_cndmask_b32_e32 v0, v0, v5, vcc
	v_sub_u32_e32 v5, v4, v3
	v_cndmask_b32_e32 v4, v4, v5, vcc
	v_add_u32_e32 v5, 1, v0
	v_cmp_ge_u32_e32 vcc, v4, v3
	v_add_u32_e32 v4, 1, v6
	s_nop 0
	v_cndmask_b32_e32 v0, v0, v5, vcc
	v_mul_lo_u32 v5, v3, v0
	v_add_u32_e32 v3, v5, v3
	v_cmp_ne_u32_e32 vcc, v4, v3
	s_and_saveexec_b64 s[8:9], vcc
	s_xor_b64 s[34:35], exec, s[8:9]
	s_cbranch_execz .LBB0_638
	v_readlane_b32 s8, v253, 62
	v_readlane_b32 s9, v253, 63
	s_waitcnt lgkmcnt(0)
	s_nop 3
	global_load_dword v2, v1, s[8:9] sc1
	s_waitcnt vmcnt(0)
	v_cmp_eq_u32_e32 vcc, v2, v0
	s_and_saveexec_b64 s[38:39], vcc
	s_cbranch_execz .LBB0_637
	s_mov_b32 s8, 1
	s_mov_b64 s[40:41], 0
	s_branch .LBB0_628

; DI unsigned xb_ld(unsigned* p) { return __hip_atomic_load(p, __ATOMIC_RELAXED, __HIP_MEMORY_SCOPE_AGENT); }
; DI unsigned xb_add(unsigned* p, unsigned v) { return __hip_atomic_fetch_add(p, v, __ATOMIC_RELAXED, __HIP_MEMORY_SCOPE_AGENT); }
; #define XB_SPIN(cond, bar) do { unsigned _sp = 0; while (cond) { \
;     if ((++_sp & 255u) == 0u) { if (xb_ld(&(bar)[XB_TMO])) break; if (_sp > XB_SPIN_CAP) { atomicAdd(&(bar)[XB_TMO], 1u); break; } } } } while (0)
; DI void xcd_barrier(const XcdBarrier& b) {
;     ...
;     unsigned nloc = b.st[0], nx = b.st[1];
;     if (nloc == 0u) { xcd_barrier_complete(bar, b.x, nloc, nx); b.st[0] = nloc; b.st[1] = nx; }
;     const unsigned old = xb_add(&bar[XB_XSUB(b.x)], 1u);
;     const unsigned gen = old / nloc;
;     if (old + 1u == (gen + 1u) * nloc) {
;       __builtin_amdgcn_fence(__ATOMIC_RELEASE, "agent");
;       asm volatile("s_waitcnt vmcnt(0)" ::: "memory");
;       const unsigned og = xb_add(&bar[XB_TOP], 1u);
;       const unsigned tg = og / nx;
;       if (og + 1u == (tg + 1u) * nx) xb_add(&bar[XB_TOPGEN], 1u);
;       else XB_SPIN(xb_ld(&bar[XB_TOPGEN]) == tg, bar);
;       __builtin_amdgcn_fence(__ATOMIC_ACQUIRE, "agent");
;       xb_add(&bar[XB_XGEN(b.x)], 1u);
;       asm volatile("s_waitcnt vmcnt(0)" ::: "memory");
;     } else {
;       XB_SPIN(xb_ld(&bar[XB_XGEN(b.x)]) == gen, bar);
;       __builtin_amdgcn_fence(__ATOMIC_ACQUIRE, "agent");
;       asm volatile("s_waitcnt vmcnt(0)" ::: "memory");
;     }
.LBB0_809:
	s_or_b64 exec, exec, s[34:35]
	v_cvt_f32_u32_e32 v5, v3
	s_waitcnt vmcnt(0)
	v_readfirstlane_b32 s6, v4
	v_sub_u32_e32 v4, 0, v3
	v_rcp_iflag_f32_e32 v5, v5
	v_add_u32_e32 v6, s6, v0
	v_mul_f32_e32 v5, 0x4f7ffffe, v5
	v_cvt_u32_f32_e32 v5, v5
	v_mul_lo_u32 v0, v4, v5
	v_mul_hi_u32 v0, v5, v0
	v_add_u32_e32 v0, v5, v0
	v_mul_hi_u32 v0, v6, v0
	v_mul_lo_u32 v4, v0, v3
	v_sub_u32_e32 v4, v6, v4
	v_add_u32_e32 v5, 1, v0
	v_cmp_ge_u32_e32 vcc, v4, v3
	s_nop 1
	v_cndmask_b32_e32 v0, v0, v5, vcc
	v_sub_u32_e32 v5, v4, v3
	v_cndmask_b32_e32 v4, v4, v5, vcc
	v_add_u32_e32 v5, 1, v0
	v_cmp_ge_u32_e32 vcc, v4, v3
	v_add_u32_e32 v4, 1, v6
	s_nop 0
	v_cndmask_b32_e32 v0, v0, v5, vcc
	v_mul_lo_u32 v5, v3, v0
	v_add_u32_e32 v3, v5, v3
	v_cmp_ne_u32_e32 vcc, v4, v3
	s_and_saveexec_b64 s[6:7], vcc
	s_xor_b64 s[34:35], exec, s[6:7]
	s_cbranch_execz .LBB0_823
	v_readlane_b32 s6, v253, 62
	v_readlane_b32 s7, v253, 63
	s_waitcnt lgkmcnt(0)
	s_nop 3
	global_load_dword v2, v1, s[6:7] sc1
	s_waitcnt vmcnt(0)
	v_cmp_eq_u32_e32 vcc, v2, v0
	s_and_saveexec_b64 s[38:39], vcc
	s_cbranch_execz .LBB0_822
	s_mov_b32 s6, 1
	s_mov_b64 s[40:41], 0
	s_branch .LBB0_813

; DI unsigned xb_ld(unsigned* p) { return __hip_atomic_load(p, __ATOMIC_RELAXED, __HIP_MEMORY_SCOPE_AGENT); }
; DI unsigned xb_add(unsigned* p, unsigned v) { return __hip_atomic_fetch_add(p, v, __ATOMIC_RELAXED, __HIP_MEMORY_SCOPE_AGENT); }
; #define XB_SPIN(cond, bar) do { unsigned _sp = 0; while (cond) { \
;     if ((++_sp & 255u) == 0u) { if (xb_ld(&(bar)[XB_TMO])) break; if (_sp > XB_SPIN_CAP) { atomicAdd(&(bar)[XB_TMO], 1u); break; } } } } while (0)
; DI void xcd_barrier(const XcdBarrier& b) {
;     ...
;     unsigned nloc = b.st[0], nx = b.st[1];
;     if (nloc == 0u) { xcd_barrier_complete(bar, b.x, nloc, nx); b.st[0] = nloc; b.st[1] = nx; }
;     const unsigned old = xb_add(&bar[XB_XSUB(b.x)], 1u);
;     const unsigned gen = old / nloc;
;     if (old + 1u == (gen + 1u) * nloc) {
;       __builtin_amdgcn_fence(__ATOMIC_RELEASE, "agent");
;       asm volatile("s_waitcnt vmcnt(0)" ::: "memory");
;       const unsigned og = xb_add(&bar[XB_TOP], 1u);
;       const unsigned tg = og / nx;
;       if (og + 1u == (tg + 1u) * nx) xb_add(&bar[XB_TOPGEN], 1u);
;       else XB_SPIN(xb_ld(&bar[XB_TOPGEN]) == tg, bar);
;       __builtin_amdgcn_fence(__ATOMIC_ACQUIRE, "agent");
;       xb_add(&bar[XB_XGEN(b.x)], 1u);
;       asm volatile("s_waitcnt vmcnt(0)" ::: "memory");
;     } else {
;       XB_SPIN(xb_ld(&bar[XB_XGEN(b.x)]) == gen, bar);
;       __builtin_amdgcn_fence(__ATOMIC_ACQUIRE, "agent");
;       asm volatile("s_waitcnt vmcnt(0)" ::: "memory");
;     }
.LBB0_1160:
	s_or_b64 exec, exec, s[34:35]
	v_cvt_f32_u32_e32 v5, v3
	s_waitcnt vmcnt(0)
	v_readfirstlane_b32 s2, v4
	v_sub_u32_e32 v4, 0, v3
	v_rcp_iflag_f32_e32 v5, v5
	v_add_u32_e32 v6, s2, v0
	v_mul_f32_e32 v5, 0x4f7ffffe, v5
	v_cvt_u32_f32_e32 v5, v5
	v_mul_lo_u32 v0, v4, v5
	v_mul_hi_u32 v0, v5, v0
	v_add_u32_e32 v0, v5, v0
	v_mul_hi_u32 v0, v6, v0
	v_mul_lo_u32 v4, v0, v3
	v_sub_u32_e32 v4, v6, v4
	v_add_u32_e32 v5, 1, v0
	v_cmp_ge_u32_e32 vcc, v4, v3
	s_nop 1
	v_cndmask_b32_e32 v0, v0, v5, vcc
	v_sub_u32_e32 v5, v4, v3
	v_cndmask_b32_e32 v4, v4, v5, vcc
	v_add_u32_e32 v5, 1, v0
	v_cmp_ge_u32_e32 vcc, v4, v3
	v_add_u32_e32 v4, 1, v6
	s_nop 0
	v_cndmask_b32_e32 v0, v0, v5, vcc
	v_mul_lo_u32 v5, v3, v0
	v_add_u32_e32 v3, v5, v3
	v_cmp_ne_u32_e32 vcc, v4, v3
	s_and_saveexec_b64 s[6:7], vcc
	s_xor_b64 s[34:35], exec, s[6:7]
	s_cbranch_execz .LBB0_1174
	v_readlane_b32 s6, v253, 62
	v_readlane_b32 s7, v253, 63
	s_waitcnt lgkmcnt(0)
	s_nop 3
	global_load_dword v2, v1, s[6:7] sc1
	s_waitcnt vmcnt(0)
	v_cmp_eq_u32_e32 vcc, v2, v0
	s_and_saveexec_b64 s[38:39], vcc
	s_cbranch_execz .LBB0_1173
	s_mov_b32 s2, 1
	s_mov_b64 s[40:41], 0
	s_branch .LBB0_1164
